# stack j + grid-barrier release polls issued back to back (s_sleep removed from the spin loops)
# speedup vs baseline: 1.0088x; 1.0088x over previous
; __global__ void __launch_bounds__(512) fwd_megakernel(Params p) {
;     ...
;     if (p.ph_lo < 0) grid.sync();
.LBB0_14:
	global_load_dword v2, v0, s[2:3] offset:32 sc1
	s_waitcnt vmcnt(0)
	v_and_b32_e32 v2, 0xffff0000, v2
	v_cmp_ne_u32_e32 vcc, v2, v1
	s_or_b64 s[4:5], vcc, s[4:5]
	s_andn2_b64 exec, exec, s[4:5]
	s_cbranch_execnz .LBB0_14

; __device__ __forceinline__ unsigned xb_ld(unsigned* p)              { return __hip_atomic_load(p, __ATOMIC_RELAXED, __HIP_MEMORY_SCOPE_AGENT); }
; __device__ __forceinline__ void xcd_barrier_complete(unsigned* bar, unsigned x, unsigned& nloc, unsigned& nx) {
;     const unsigned G = gridDim.x * gridDim.y * gridDim.z;
;     unsigned sum, cnt, mine, sp = 0u;
;     for (;;) {
;         sum = 0u; cnt = 0u; mine = 0u;
; #pragma unroll
;         for (unsigned j = 0; j < 16; ++j) { const unsigned c = xb_ld(&bar[XB_XCNT(j)]); sum += c; cnt += (c > 0u) ? 1u : 0u; mine = (j == x) ? c : mine; }
;         if (sum == G) break;
;         __builtin_amdgcn_s_sleep(1);
;         if ((++sp & 255u) == 0u) { if (xb_ld(&bar[XB_TMO])) break; if (sp > XB_SPIN_CAP) { atomicAdd(&bar[XB_TMO], 1u); break; } }
;     }
;     nloc = mine > 0u ? mine : 1u; nx = cnt > 0u ? cnt : 1u;
; }
.LBB0_2093:
	global_load_dword v15, v16, s[4:5] sc1
	s_waitcnt lgkmcnt(0)
	global_load_dword v0, v16, s[6:7] sc1
	global_load_dword v1, v16, s[10:11] sc1
	global_load_dword v2, v16, s[14:15] sc1
	global_load_dword v3, v16, s[16:17] sc1
	global_load_dword v4, v16, s[18:19] sc1
	global_load_dword v5, v16, s[20:21] sc1
	global_load_dword v6, v16, s[22:23] sc1
	global_load_dword v7, v16, s[24:25] sc1
	global_load_dword v8, v16, s[26:27] sc1
	global_load_dword v9, v16, s[28:29] sc1
	global_load_dword v10, v16, s[30:31] sc1
	global_load_dword v11, v16, s[34:35] sc1
	global_load_dword v12, v16, s[36:37] sc1
	global_load_dword v13, v16, s[38:39] sc1
	global_load_dword v14, v16, s[40:41] sc1
	s_mov_b64 s[42:43], -1
	s_mov_b64 s[44:45], -1
	s_waitcnt vmcnt(14)
	v_add_u32_e32 v17, v0, v15
	s_waitcnt vmcnt(13)
	v_add_u32_e32 v17, v17, v1
	s_waitcnt vmcnt(12)
	v_add_u32_e32 v17, v17, v2
	s_waitcnt vmcnt(11)
	v_add_u32_e32 v17, v17, v3
	s_waitcnt vmcnt(10)
	v_add_u32_e32 v17, v17, v4
	s_waitcnt vmcnt(9)
	v_add_u32_e32 v17, v17, v5
	s_waitcnt vmcnt(8)
	v_add_u32_e32 v17, v17, v6
	s_waitcnt vmcnt(7)
	v_add_u32_e32 v17, v17, v7
	s_waitcnt vmcnt(6)
	v_add_u32_e32 v17, v17, v8
	s_waitcnt vmcnt(5)
	v_add_u32_e32 v17, v17, v9
	s_waitcnt vmcnt(4)
	v_add_u32_e32 v17, v17, v10
	s_waitcnt vmcnt(3)
	v_add_u32_e32 v17, v17, v11
	s_waitcnt vmcnt(2)
	v_add_u32_e32 v17, v17, v12
	s_waitcnt vmcnt(1)
	v_add_u32_e32 v17, v17, v13
	s_waitcnt vmcnt(0)
	v_add_u32_e32 v17, v17, v14
	v_cmp_eq_u32_e32 vcc, s13, v17
	s_cbranch_vccnz .LBB0_2092
	s_and_b32 s42, s33, 0xff
	s_cmp_eq_u32 s42, 0
	s_mov_b64 s[42:43], -1
	s_mov_b64 s[46:47], -1
	s_cbranch_scc1 .LBB0_2097
	s_and_b64 vcc, exec, s[46:47]
	s_cbranch_vccz .LBB0_2092

; __device__ __forceinline__ unsigned xb_ld(unsigned* p)              { return __hip_atomic_load(p, __ATOMIC_RELAXED, __HIP_MEMORY_SCOPE_AGENT); }
; __device__ __forceinline__ unsigned xb_add(unsigned* p, unsigned v) { return __hip_atomic_fetch_add(p, v, __ATOMIC_RELAXED, __HIP_MEMORY_SCOPE_AGENT); }
; #define XB_SPIN(cond, bar) do { unsigned _sp = 0; while (cond) { __builtin_amdgcn_s_sleep(1); \
;     if ((++_sp & 255u) == 0u) { if (xb_ld(&(bar)[XB_TMO])) break; if (_sp > XB_SPIN_CAP) { atomicAdd(&(bar)[XB_TMO], 1u); break; } } } } while (0)
; __device__ __forceinline__ void xcd_barrier(const XcdBarrier& b) {
;     ...
;             else XB_SPIN(xb_ld(&bar[XB_TOPGEN]) == tg, bar);
;             __builtin_amdgcn_fence(__ATOMIC_ACQUIRE, "agent");
;             xb_add(&bar[XB_XGEN(b.x)], 1u);
;             asm volatile("s_waitcnt vmcnt(0)" ::: "memory");
;         } else {
;             XB_SPIN(xb_ld(&bar[XB_XGEN(b.x)]) == gen, bar);
.LBB0_2111:
	s_and_b32 s22, s13, 0xff
	s_mov_b64 s[20:21], -1
	s_cmp_lg_u32 s22, 0
	s_mov_b64 s[24:25], -1
	s_cbranch_scc0 .LBB0_2114
	s_and_b64 vcc, exec, s[24:25]
	s_cbranch_vccz .LBB0_2110

; __device__ __forceinline__ unsigned xb_ld(unsigned* p)              { return __hip_atomic_load(p, __ATOMIC_RELAXED, __HIP_MEMORY_SCOPE_AGENT); }
; __device__ __forceinline__ unsigned xb_add(unsigned* p, unsigned v) { return __hip_atomic_fetch_add(p, v, __ATOMIC_RELAXED, __HIP_MEMORY_SCOPE_AGENT); }
; #define XB_SPIN(cond, bar) do { unsigned _sp = 0; while (cond) { __builtin_amdgcn_s_sleep(1); \
;     if ((++_sp & 255u) == 0u) { if (xb_ld(&(bar)[XB_TMO])) break; if (_sp > XB_SPIN_CAP) { atomicAdd(&(bar)[XB_TMO], 1u); break; } } } } while (0)
; __device__ __forceinline__ void xcd_barrier(const XcdBarrier& b) {
;     ...
;             else XB_SPIN(xb_ld(&bar[XB_TOPGEN]) == tg, bar);
;             __builtin_amdgcn_fence(__ATOMIC_ACQUIRE, "agent");
;             xb_add(&bar[XB_XGEN(b.x)], 1u);
;             asm volatile("s_waitcnt vmcnt(0)" ::: "memory");
;         } else {
;             XB_SPIN(xb_ld(&bar[XB_XGEN(b.x)]) == gen, bar);
.LBB0_2128:
	s_and_b32 s20, s13, 0xff
	s_cmp_lg_u32 s20, 0
	s_mov_b64 s[22:23], -1
	s_cbranch_scc0 .LBB0_2131
	s_mov_b64 s[24:25], -1
	s_and_b64 vcc, exec, s[22:23]
	s_cbranch_vccz .LBB0_2127

; __device__ __forceinline__ unsigned xb_ld(unsigned* p)              { return __hip_atomic_load(p, __ATOMIC_RELAXED, __HIP_MEMORY_SCOPE_AGENT); }
; __device__ __forceinline__ void xcd_barrier_complete(unsigned* bar, unsigned x, unsigned& nloc, unsigned& nx) {
;     const unsigned G = gridDim.x * gridDim.y * gridDim.z;
;     unsigned sum, cnt, mine, sp = 0u;
;     for (;;) {
;         sum = 0u; cnt = 0u; mine = 0u;
; #pragma unroll
;         for (unsigned j = 0; j < 16; ++j) { const unsigned c = xb_ld(&bar[XB_XCNT(j)]); sum += c; cnt += (c > 0u) ? 1u : 0u; mine = (j == x) ? c : mine; }
;         if (sum == G) break;
;         __builtin_amdgcn_s_sleep(1);
;         if ((++sp & 255u) == 0u) { if (xb_ld(&bar[XB_TMO])) break; if (sp > XB_SPIN_CAP) { atomicAdd(&bar[XB_TMO], 1u); break; } }
;     }
;     nloc = mine > 0u ? mine : 1u; nx = cnt > 0u ? cnt : 1u;
; }
.LBB0_2158:
	v_readlane_b32 s10, v251, 51
	v_readlane_b32 s11, v251, 52
	v_readlane_b32 s7, v255, 18
	s_mov_b64 s[38:39], -1
	s_waitcnt lgkmcnt(0)
	s_nop 1
	global_load_dword v0, v179, s[10:11] sc1
	v_readlane_b32 s10, v251, 53
	v_readlane_b32 s11, v251, 54
	s_nop 4
	global_load_dword v1, v179, s[10:11] sc1
	v_readlane_b32 s10, v251, 55
	v_readlane_b32 s11, v251, 56
	s_waitcnt vmcnt(0)
	v_add_u32_e32 v16, v1, v0
	s_nop 2
	global_load_dword v2, v179, s[10:11] sc1
	v_readlane_b32 s10, v251, 57
	v_readlane_b32 s11, v251, 58
	s_waitcnt vmcnt(0)
	v_add_u32_e32 v16, v16, v2
	s_nop 2
	global_load_dword v3, v179, s[10:11] sc1
	v_readlane_b32 s10, v251, 59
	v_readlane_b32 s11, v251, 60
	s_waitcnt vmcnt(0)
	v_add_u32_e32 v16, v16, v3
	s_nop 2
	global_load_dword v4, v179, s[10:11] sc1
	v_readlane_b32 s10, v251, 61
	v_readlane_b32 s11, v251, 62
	s_waitcnt vmcnt(0)
	v_add_u32_e32 v16, v16, v4
	s_nop 2
	global_load_dword v5, v179, s[10:11] sc1
	v_readlane_b32 s10, v251, 63
	v_readlane_b32 s11, v252, 0
	s_waitcnt vmcnt(0)
	v_add_u32_e32 v16, v16, v5
	s_nop 2
	global_load_dword v6, v179, s[10:11] sc1
	v_readlane_b32 s10, v252, 1
	v_readlane_b32 s11, v252, 2
	s_waitcnt vmcnt(0)
	v_add_u32_e32 v16, v16, v6
	s_nop 2
	global_load_dword v7, v179, s[10:11] sc1
	v_readlane_b32 s10, v252, 3
	v_readlane_b32 s11, v252, 4
	s_waitcnt vmcnt(0)
	v_add_u32_e32 v16, v16, v7
	s_nop 2
	global_load_dword v8, v179, s[10:11] sc1
	v_readlane_b32 s10, v252, 5
	v_readlane_b32 s11, v252, 6
	s_waitcnt vmcnt(0)
	v_add_u32_e32 v16, v16, v8
	s_nop 2
	global_load_dword v9, v179, s[10:11] sc1
	v_readlane_b32 s10, v252, 7
	v_readlane_b32 s11, v252, 8
	s_waitcnt vmcnt(0)
	v_add_u32_e32 v16, v16, v9
	s_nop 2
	global_load_dword v10, v179, s[10:11] sc1
	v_readlane_b32 s10, v252, 9
	v_readlane_b32 s11, v252, 10
	s_waitcnt vmcnt(0)
	v_add_u32_e32 v16, v16, v10
	s_nop 2
	global_load_dword v11, v179, s[10:11] sc1
	v_readlane_b32 s10, v252, 11
	v_readlane_b32 s11, v252, 12
	s_waitcnt vmcnt(0)
	v_add_u32_e32 v16, v16, v11
	s_nop 2
	global_load_dword v12, v179, s[10:11] sc1
	v_readlane_b32 s10, v252, 13
	v_readlane_b32 s11, v252, 14
	s_waitcnt vmcnt(0)
	v_add_u32_e32 v16, v16, v12
	s_nop 2
	global_load_dword v13, v179, s[10:11] sc1
	v_readlane_b32 s10, v252, 15
	v_readlane_b32 s11, v252, 16
	s_waitcnt vmcnt(0)
	v_add_u32_e32 v16, v16, v13
	s_nop 2
	global_load_dword v14, v179, s[10:11] sc1
	v_readlane_b32 s10, v252, 17
	v_readlane_b32 s11, v252, 18
	s_waitcnt vmcnt(0)
	v_add_u32_e32 v16, v16, v14
	s_nop 2
	global_load_dword v15, v179, s[10:11] sc1
	s_mov_b64 s[10:11], -1
	s_waitcnt vmcnt(0)
	v_add_u32_e32 v16, v16, v15
	v_cmp_eq_u32_e32 vcc, s7, v16
	s_cbranch_vccnz .LBB0_2157
	s_and_b32 s7, s6, 0xff
	s_cmp_eq_u32 s7, 0
	s_mov_b64 s[40:41], -1
	s_cbranch_scc1 .LBB0_2162
	s_and_b64 vcc, exec, s[40:41]
	s_cbranch_vccz .LBB0_2157

; __device__ __forceinline__ unsigned xb_ld(unsigned* p)              { return __hip_atomic_load(p, __ATOMIC_RELAXED, __HIP_MEMORY_SCOPE_AGENT); }
; __device__ __forceinline__ unsigned xb_add(unsigned* p, unsigned v) { return __hip_atomic_fetch_add(p, v, __ATOMIC_RELAXED, __HIP_MEMORY_SCOPE_AGENT); }
; #define XB_SPIN(cond, bar) do { unsigned _sp = 0; while (cond) { __builtin_amdgcn_s_sleep(1); \
;     if ((++_sp & 255u) == 0u) { if (xb_ld(&(bar)[XB_TMO])) break; if (_sp > XB_SPIN_CAP) { atomicAdd(&(bar)[XB_TMO], 1u); break; } } } } while (0)
; __device__ __forceinline__ void xcd_barrier(const XcdBarrier& b) {
;     ...
;             else XB_SPIN(xb_ld(&bar[XB_TOPGEN]) == tg, bar);
;             __builtin_amdgcn_fence(__ATOMIC_ACQUIRE, "agent");
;             xb_add(&bar[XB_XGEN(b.x)], 1u);
;             asm volatile("s_waitcnt vmcnt(0)" ::: "memory");
;         } else {
;             XB_SPIN(xb_ld(&bar[XB_XGEN(b.x)]) == gen, bar);
.LBB0_2176:
	s_and_b32 s7, s6, 0xff
	s_mov_b64 s[44:45], -1
	s_cmp_lg_u32 s7, 0
	s_mov_b64 s[48:49], -1
	s_cbranch_scc0 .LBB0_2179
	s_and_b64 vcc, exec, s[48:49]
	s_cbranch_vccz .LBB0_2175

; __device__ __forceinline__ unsigned xb_ld(unsigned* p)              { return __hip_atomic_load(p, __ATOMIC_RELAXED, __HIP_MEMORY_SCOPE_AGENT); }
; __device__ __forceinline__ void xcd_barrier_complete(unsigned* bar, unsigned x, unsigned& nloc, unsigned& nx) {
;     const unsigned G = gridDim.x * gridDim.y * gridDim.z;
;     unsigned sum, cnt, mine, sp = 0u;
;     for (;;) {
;         sum = 0u; cnt = 0u; mine = 0u;
; #pragma unroll
;         for (unsigned j = 0; j < 16; ++j) { const unsigned c = xb_ld(&bar[XB_XCNT(j)]); sum += c; cnt += (c > 0u) ? 1u : 0u; mine = (j == x) ? c : mine; }
;         if (sum == G) break;
;         __builtin_amdgcn_s_sleep(1);
;         if ((++sp & 255u) == 0u) { if (xb_ld(&bar[XB_TMO])) break; if (sp > XB_SPIN_CAP) { atomicAdd(&bar[XB_TMO], 1u); break; } }
;     }
;     nloc = mine > 0u ? mine : 1u; nx = cnt > 0u ? cnt : 1u;
; }
.LBB0_2508:
	v_readlane_b32 s2, v251, 51
	v_readlane_b32 s3, v251, 52
	v_readlane_b32 s7, v255, 18
	s_mov_b64 s[38:39], -1
	s_waitcnt lgkmcnt(0)
	s_nop 1
	global_load_dword v0, v179, s[2:3] sc1
	v_readlane_b32 s2, v251, 53
	v_readlane_b32 s3, v251, 54
	s_nop 4
	global_load_dword v1, v179, s[2:3] sc1
	v_readlane_b32 s2, v251, 55
	v_readlane_b32 s3, v251, 56
	s_waitcnt vmcnt(0)
	v_add_u32_e32 v16, v1, v0
	s_nop 2
	global_load_dword v2, v179, s[2:3] sc1
	v_readlane_b32 s2, v251, 57
	v_readlane_b32 s3, v251, 58
	s_waitcnt vmcnt(0)
	v_add_u32_e32 v16, v16, v2
	s_nop 2
	global_load_dword v3, v179, s[2:3] sc1
	v_readlane_b32 s2, v251, 59
	v_readlane_b32 s3, v251, 60
	s_waitcnt vmcnt(0)
	v_add_u32_e32 v16, v16, v3
	s_nop 2
	global_load_dword v4, v179, s[2:3] sc1
	v_readlane_b32 s2, v251, 61
	v_readlane_b32 s3, v251, 62
	s_waitcnt vmcnt(0)
	v_add_u32_e32 v16, v16, v4
	s_nop 2
	global_load_dword v5, v179, s[2:3] sc1
	v_readlane_b32 s2, v251, 63
	v_readlane_b32 s3, v252, 0
	s_waitcnt vmcnt(0)
	v_add_u32_e32 v16, v16, v5
	s_nop 2
	global_load_dword v6, v179, s[2:3] sc1
	v_readlane_b32 s2, v252, 1
	v_readlane_b32 s3, v252, 2
	s_waitcnt vmcnt(0)
	v_add_u32_e32 v16, v16, v6
	s_nop 2
	global_load_dword v7, v179, s[2:3] sc1
	v_readlane_b32 s2, v252, 3
	v_readlane_b32 s3, v252, 4
	s_waitcnt vmcnt(0)
	v_add_u32_e32 v16, v16, v7
	s_nop 2
	global_load_dword v8, v179, s[2:3] sc1
	v_readlane_b32 s2, v252, 5
	v_readlane_b32 s3, v252, 6
	s_waitcnt vmcnt(0)
	v_add_u32_e32 v16, v16, v8
	s_nop 2
	global_load_dword v9, v179, s[2:3] sc1
	v_readlane_b32 s2, v252, 7
	v_readlane_b32 s3, v252, 8
	s_waitcnt vmcnt(0)
	v_add_u32_e32 v16, v16, v9
	s_nop 2
	global_load_dword v10, v179, s[2:3] sc1
	v_readlane_b32 s2, v252, 9
	v_readlane_b32 s3, v252, 10
	s_waitcnt vmcnt(0)
	v_add_u32_e32 v16, v16, v10
	s_nop 2
	global_load_dword v11, v179, s[2:3] sc1
	v_readlane_b32 s2, v252, 11
	v_readlane_b32 s3, v252, 12
	s_waitcnt vmcnt(0)
	v_add_u32_e32 v16, v16, v11
	s_nop 2
	global_load_dword v12, v179, s[2:3] sc1
	v_readlane_b32 s2, v252, 13
	v_readlane_b32 s3, v252, 14
	s_waitcnt vmcnt(0)
	v_add_u32_e32 v16, v16, v12
	s_nop 2
	global_load_dword v13, v179, s[2:3] sc1
	v_readlane_b32 s2, v252, 15
	v_readlane_b32 s3, v252, 16
	s_waitcnt vmcnt(0)
	v_add_u32_e32 v16, v16, v13
	s_nop 2
	global_load_dword v14, v179, s[2:3] sc1
	v_readlane_b32 s2, v252, 17
	v_readlane_b32 s3, v252, 18
	s_waitcnt vmcnt(0)
	v_add_u32_e32 v16, v16, v14
	s_nop 2
	global_load_dword v15, v179, s[2:3] sc1
	s_mov_b64 s[2:3], -1
	s_waitcnt vmcnt(0)
	v_add_u32_e32 v16, v16, v15
	v_cmp_eq_u32_e32 vcc, s7, v16
	s_cbranch_vccnz .LBB0_2507
	s_and_b32 s2, s6, 0xff
	s_cmp_eq_u32 s2, 0
	s_mov_b64 s[2:3], -1
	s_mov_b64 s[40:41], -1
	s_cbranch_scc1 .LBB0_2512
	s_and_b64 vcc, exec, s[40:41]
	s_cbranch_vccz .LBB0_2507

; __device__ __forceinline__ unsigned xb_ld(unsigned* p)              { return __hip_atomic_load(p, __ATOMIC_RELAXED, __HIP_MEMORY_SCOPE_AGENT); }
; __device__ __forceinline__ void xcd_barrier_complete(unsigned* bar, unsigned x, unsigned& nloc, unsigned& nx) {
;     const unsigned G = gridDim.x * gridDim.y * gridDim.z;
;     unsigned sum, cnt, mine, sp = 0u;
;     for (;;) {
;         sum = 0u; cnt = 0u; mine = 0u;
; #pragma unroll
;         for (unsigned j = 0; j < 16; ++j) { const unsigned c = xb_ld(&bar[XB_XCNT(j)]); sum += c; cnt += (c > 0u) ? 1u : 0u; mine = (j == x) ? c : mine; }
;         if (sum == G) break;
;         __builtin_amdgcn_s_sleep(1);
;         if ((++sp & 255u) == 0u) { if (xb_ld(&bar[XB_TMO])) break; if (sp > XB_SPIN_CAP) { atomicAdd(&bar[XB_TMO], 1u); break; } }
;     }
;     nloc = mine > 0u ? mine : 1u; nx = cnt > 0u ? cnt : 1u;
; }
.LBB0_3214:
	v_readlane_b32 s22, v251, 51
	v_readlane_b32 s23, v251, 52
	v_readlane_b32 s7, v255, 18
	s_mov_b64 s[38:39], -1
	s_mov_b64 s[40:41], -1
	s_waitcnt lgkmcnt(0)
	s_nop 0
	global_load_dword v0, v179, s[22:23] sc1
	v_readlane_b32 s22, v251, 53
	v_readlane_b32 s23, v251, 54
	s_nop 4
	global_load_dword v1, v179, s[22:23] sc1
	v_readlane_b32 s22, v251, 55
	v_readlane_b32 s23, v251, 56
	s_waitcnt vmcnt(0)
	v_add_u32_e32 v16, v1, v0
	s_nop 2
	global_load_dword v2, v179, s[22:23] sc1
	v_readlane_b32 s22, v251, 57
	v_readlane_b32 s23, v251, 58
	s_waitcnt vmcnt(0)
	v_add_u32_e32 v16, v16, v2
	s_nop 2
	global_load_dword v3, v179, s[22:23] sc1
	v_readlane_b32 s22, v251, 59
	v_readlane_b32 s23, v251, 60
	s_waitcnt vmcnt(0)
	v_add_u32_e32 v16, v16, v3
	s_nop 2
	global_load_dword v4, v179, s[22:23] sc1
	v_readlane_b32 s22, v251, 61
	v_readlane_b32 s23, v251, 62
	s_waitcnt vmcnt(0)
	v_add_u32_e32 v16, v16, v4
	s_nop 2
	global_load_dword v5, v179, s[22:23] sc1
	v_readlane_b32 s22, v251, 63
	v_readlane_b32 s23, v252, 0
	s_waitcnt vmcnt(0)
	v_add_u32_e32 v16, v16, v5
	s_nop 2
	global_load_dword v6, v179, s[22:23] sc1
	v_readlane_b32 s22, v252, 1
	v_readlane_b32 s23, v252, 2
	s_waitcnt vmcnt(0)
	v_add_u32_e32 v16, v16, v6
	s_nop 2
	global_load_dword v7, v179, s[22:23] sc1
	v_readlane_b32 s22, v252, 3
	v_readlane_b32 s23, v252, 4
	s_waitcnt vmcnt(0)
	v_add_u32_e32 v16, v16, v7
	s_nop 2
	global_load_dword v8, v179, s[22:23] sc1
	v_readlane_b32 s22, v252, 5
	v_readlane_b32 s23, v252, 6
	s_waitcnt vmcnt(0)
	v_add_u32_e32 v16, v16, v8
	s_nop 2
	global_load_dword v9, v179, s[22:23] sc1
	v_readlane_b32 s22, v252, 7
	v_readlane_b32 s23, v252, 8
	s_waitcnt vmcnt(0)
	v_add_u32_e32 v16, v16, v9
	s_nop 2
	global_load_dword v10, v179, s[22:23] sc1
	v_readlane_b32 s22, v252, 9
	v_readlane_b32 s23, v252, 10
	s_waitcnt vmcnt(0)
	v_add_u32_e32 v16, v16, v10
	s_nop 2
	global_load_dword v11, v179, s[22:23] sc1
	v_readlane_b32 s22, v252, 11
	v_readlane_b32 s23, v252, 12
	s_waitcnt vmcnt(0)
	v_add_u32_e32 v16, v16, v11
	s_nop 2
	global_load_dword v12, v179, s[22:23] sc1
	v_readlane_b32 s22, v252, 13
	v_readlane_b32 s23, v252, 14
	s_waitcnt vmcnt(0)
	v_add_u32_e32 v16, v16, v12
	s_nop 2
	global_load_dword v13, v179, s[22:23] sc1
	v_readlane_b32 s22, v252, 15
	v_readlane_b32 s23, v252, 16
	s_waitcnt vmcnt(0)
	v_add_u32_e32 v16, v16, v13
	s_nop 2
	global_load_dword v14, v179, s[22:23] sc1
	v_readlane_b32 s22, v252, 17
	v_readlane_b32 s23, v252, 18
	s_waitcnt vmcnt(0)
	v_add_u32_e32 v16, v16, v14
	s_nop 2
	global_load_dword v15, v179, s[22:23] sc1
	s_waitcnt vmcnt(0)
	v_add_u32_e32 v16, v16, v15
	v_cmp_eq_u32_e32 vcc, s7, v16
	s_cbranch_vccnz .LBB0_3213
	s_and_b32 s7, s6, 0xff
	s_cmp_eq_u32 s7, 0
	s_mov_b64 s[42:43], -1
	s_cbranch_scc1 .LBB0_3218
	s_and_b64 vcc, exec, s[42:43]
	s_cbranch_vccz .LBB0_3213

; __device__ __forceinline__ unsigned xb_ld(unsigned* p)              { return __hip_atomic_load(p, __ATOMIC_RELAXED, __HIP_MEMORY_SCOPE_AGENT); }
; __device__ __forceinline__ unsigned xb_add(unsigned* p, unsigned v) { return __hip_atomic_fetch_add(p, v, __ATOMIC_RELAXED, __HIP_MEMORY_SCOPE_AGENT); }
; #define XB_SPIN(cond, bar) do { unsigned _sp = 0; while (cond) { __builtin_amdgcn_s_sleep(1); \
;     if ((++_sp & 255u) == 0u) { if (xb_ld(&(bar)[XB_TMO])) break; if (_sp > XB_SPIN_CAP) { atomicAdd(&(bar)[XB_TMO], 1u); break; } } } } while (0)
; __device__ __forceinline__ void xcd_barrier(const XcdBarrier& b) {
;     ...
;             else XB_SPIN(xb_ld(&bar[XB_TOPGEN]) == tg, bar);
;             __builtin_amdgcn_fence(__ATOMIC_ACQUIRE, "agent");
;             xb_add(&bar[XB_XGEN(b.x)], 1u);
;             asm volatile("s_waitcnt vmcnt(0)" ::: "memory");
;         } else {
;             XB_SPIN(xb_ld(&bar[XB_XGEN(b.x)]) == gen, bar);
.LBB0_3232:
	s_and_b32 s7, s6, 0xff
	s_mov_b64 s[46:47], -1
	s_cmp_lg_u32 s7, 0
	s_mov_b64 s[50:51], -1
	s_cbranch_scc0 .LBB0_3235
	s_and_b64 vcc, exec, s[50:51]
	s_cbranch_vccz .LBB0_3231

; __device__ __forceinline__ unsigned xb_ld(unsigned* p)              { return __hip_atomic_load(p, __ATOMIC_RELAXED, __HIP_MEMORY_SCOPE_AGENT); }
; __device__ __forceinline__ void xcd_barrier_complete(unsigned* bar, unsigned x, unsigned& nloc, unsigned& nx) {
;     const unsigned G = gridDim.x * gridDim.y * gridDim.z;
;     unsigned sum, cnt, mine, sp = 0u;
;     for (;;) {
;         sum = 0u; cnt = 0u; mine = 0u;
; #pragma unroll
;         for (unsigned j = 0; j < 16; ++j) { const unsigned c = xb_ld(&bar[XB_XCNT(j)]); sum += c; cnt += (c > 0u) ? 1u : 0u; mine = (j == x) ? c : mine; }
;         if (sum == G) break;
;         __builtin_amdgcn_s_sleep(1);
;         if ((++sp & 255u) == 0u) { if (xb_ld(&bar[XB_TMO])) break; if (sp > XB_SPIN_CAP) { atomicAdd(&bar[XB_TMO], 1u); break; } }
;     }
;     nloc = mine > 0u ? mine : 1u; nx = cnt > 0u ? cnt : 1u;
; }
.LBB0_3597:
	v_readlane_b32 s22, v251, 51
	v_readlane_b32 s23, v251, 52
	v_readlane_b32 s7, v255, 18
	s_mov_b64 s[38:39], -1
	s_mov_b64 s[40:41], -1
	s_waitcnt lgkmcnt(0)
	s_nop 0
	global_load_dword v0, v179, s[22:23] sc1
	v_readlane_b32 s22, v251, 53
	v_readlane_b32 s23, v251, 54
	s_nop 4
	global_load_dword v1, v179, s[22:23] sc1
	v_readlane_b32 s22, v251, 55
	v_readlane_b32 s23, v251, 56
	s_waitcnt vmcnt(0)
	v_add_u32_e32 v16, v1, v0
	s_nop 2
	global_load_dword v2, v179, s[22:23] sc1
	v_readlane_b32 s22, v251, 57
	v_readlane_b32 s23, v251, 58
	s_waitcnt vmcnt(0)
	v_add_u32_e32 v16, v16, v2
	s_nop 2
	global_load_dword v3, v179, s[22:23] sc1
	v_readlane_b32 s22, v251, 59
	v_readlane_b32 s23, v251, 60
	s_waitcnt vmcnt(0)
	v_add_u32_e32 v16, v16, v3
	s_nop 2
	global_load_dword v4, v179, s[22:23] sc1
	v_readlane_b32 s22, v251, 61
	v_readlane_b32 s23, v251, 62
	s_waitcnt vmcnt(0)
	v_add_u32_e32 v16, v16, v4
	s_nop 2
	global_load_dword v5, v179, s[22:23] sc1
	v_readlane_b32 s22, v251, 63
	v_readlane_b32 s23, v252, 0
	s_waitcnt vmcnt(0)
	v_add_u32_e32 v16, v16, v5
	s_nop 2
	global_load_dword v6, v179, s[22:23] sc1
	v_readlane_b32 s22, v252, 1
	v_readlane_b32 s23, v252, 2
	s_waitcnt vmcnt(0)
	v_add_u32_e32 v16, v16, v6
	s_nop 2
	global_load_dword v7, v179, s[22:23] sc1
	v_readlane_b32 s22, v252, 3
	v_readlane_b32 s23, v252, 4
	s_waitcnt vmcnt(0)
	v_add_u32_e32 v16, v16, v7
	s_nop 2
	global_load_dword v8, v179, s[22:23] sc1
	v_readlane_b32 s22, v252, 5
	v_readlane_b32 s23, v252, 6
	s_waitcnt vmcnt(0)
	v_add_u32_e32 v16, v16, v8
	s_nop 2
	global_load_dword v9, v179, s[22:23] sc1
	v_readlane_b32 s22, v252, 7
	v_readlane_b32 s23, v252, 8
	s_waitcnt vmcnt(0)
	v_add_u32_e32 v16, v16, v9
	s_nop 2
	global_load_dword v10, v179, s[22:23] sc1
	v_readlane_b32 s22, v252, 9
	v_readlane_b32 s23, v252, 10
	s_waitcnt vmcnt(0)
	v_add_u32_e32 v16, v16, v10
	s_nop 2
	global_load_dword v11, v179, s[22:23] sc1
	v_readlane_b32 s22, v252, 11
	v_readlane_b32 s23, v252, 12
	s_waitcnt vmcnt(0)
	v_add_u32_e32 v16, v16, v11
	s_nop 2
	global_load_dword v12, v179, s[22:23] sc1
	v_readlane_b32 s22, v252, 13
	v_readlane_b32 s23, v252, 14
	s_waitcnt vmcnt(0)
	v_add_u32_e32 v16, v16, v12
	s_nop 2
	global_load_dword v13, v179, s[22:23] sc1
	v_readlane_b32 s22, v252, 15
	v_readlane_b32 s23, v252, 16
	s_waitcnt vmcnt(0)
	v_add_u32_e32 v16, v16, v13
	s_nop 2
	global_load_dword v14, v179, s[22:23] sc1
	v_readlane_b32 s22, v252, 17
	v_readlane_b32 s23, v252, 18
	s_waitcnt vmcnt(0)
	v_add_u32_e32 v16, v16, v14
	s_nop 2
	global_load_dword v15, v179, s[22:23] sc1
	s_waitcnt vmcnt(0)
	v_add_u32_e32 v16, v16, v15
	v_cmp_eq_u32_e32 vcc, s7, v16
	s_cbranch_vccnz .LBB0_3596
	s_and_b32 s7, s4, 0xff
	s_cmp_eq_u32 s7, 0
	s_mov_b64 s[42:43], -1
	s_cbranch_scc1 .LBB0_3601
	s_and_b64 vcc, exec, s[42:43]
	s_cbranch_vccz .LBB0_3596

; __device__ __forceinline__ unsigned xb_ld(unsigned* p)              { return __hip_atomic_load(p, __ATOMIC_RELAXED, __HIP_MEMORY_SCOPE_AGENT); }
; __device__ __forceinline__ unsigned xb_add(unsigned* p, unsigned v) { return __hip_atomic_fetch_add(p, v, __ATOMIC_RELAXED, __HIP_MEMORY_SCOPE_AGENT); }
; #define XB_SPIN(cond, bar) do { unsigned _sp = 0; while (cond) { __builtin_amdgcn_s_sleep(1); \
;     if ((++_sp & 255u) == 0u) { if (xb_ld(&(bar)[XB_TMO])) break; if (_sp > XB_SPIN_CAP) { atomicAdd(&(bar)[XB_TMO], 1u); break; } } } } while (0)
; __device__ __forceinline__ void xcd_barrier(const XcdBarrier& b) {
;     ...
;             else XB_SPIN(xb_ld(&bar[XB_TOPGEN]) == tg, bar);
;             __builtin_amdgcn_fence(__ATOMIC_ACQUIRE, "agent");
;             xb_add(&bar[XB_XGEN(b.x)], 1u);
;             asm volatile("s_waitcnt vmcnt(0)" ::: "memory");
;         } else {
;             XB_SPIN(xb_ld(&bar[XB_XGEN(b.x)]) == gen, bar);
.LBB0_3615:
	s_and_b32 s7, s4, 0xff
	s_mov_b64 s[46:47], -1
	s_cmp_lg_u32 s7, 0
	s_mov_b64 s[50:51], -1
	s_cbranch_scc0 .LBB0_3618
	s_and_b64 vcc, exec, s[50:51]
	s_cbranch_vccz .LBB0_3614

; __device__ __forceinline__ unsigned xb_ld(unsigned* p)              { return __hip_atomic_load(p, __ATOMIC_RELAXED, __HIP_MEMORY_SCOPE_AGENT); }
; __device__ __forceinline__ void xcd_barrier_complete(unsigned* bar, unsigned x, unsigned& nloc, unsigned& nx) {
;     const unsigned G = gridDim.x * gridDim.y * gridDim.z;
;     unsigned sum, cnt, mine, sp = 0u;
;     for (;;) {
;         sum = 0u; cnt = 0u; mine = 0u;
; #pragma unroll
;         for (unsigned j = 0; j < 16; ++j) { const unsigned c = xb_ld(&bar[XB_XCNT(j)]); sum += c; cnt += (c > 0u) ? 1u : 0u; mine = (j == x) ? c : mine; }
;         if (sum == G) break;
;         __builtin_amdgcn_s_sleep(1);
;         if ((++sp & 255u) == 0u) { if (xb_ld(&bar[XB_TMO])) break; if (sp > XB_SPIN_CAP) { atomicAdd(&bar[XB_TMO], 1u); break; } }
;     }
;     nloc = mine > 0u ? mine : 1u; nx = cnt > 0u ? cnt : 1u;
; }
.LBB0_3658:
	v_readlane_b32 s22, v251, 51
	v_readlane_b32 s23, v251, 52
	v_readlane_b32 s14, v255, 18
	s_mov_b64 s[38:39], -1
	s_mov_b64 s[40:41], -1
	s_waitcnt lgkmcnt(0)
	s_nop 0
	global_load_dword v0, v179, s[22:23] sc1
	v_readlane_b32 s22, v251, 53
	v_readlane_b32 s23, v251, 54
	s_nop 4
	global_load_dword v1, v179, s[22:23] sc1
	v_readlane_b32 s22, v251, 55
	v_readlane_b32 s23, v251, 56
	s_waitcnt vmcnt(0)
	v_add_u32_e32 v16, v1, v0
	s_nop 2
	global_load_dword v2, v179, s[22:23] sc1
	v_readlane_b32 s22, v251, 57
	v_readlane_b32 s23, v251, 58
	s_waitcnt vmcnt(0)
	v_add_u32_e32 v16, v16, v2
	s_nop 2
	global_load_dword v3, v179, s[22:23] sc1
	v_readlane_b32 s22, v251, 59
	v_readlane_b32 s23, v251, 60
	s_waitcnt vmcnt(0)
	v_add_u32_e32 v16, v16, v3
	s_nop 2
	global_load_dword v4, v179, s[22:23] sc1
	v_readlane_b32 s22, v251, 61
	v_readlane_b32 s23, v251, 62
	s_waitcnt vmcnt(0)
	v_add_u32_e32 v16, v16, v4
	s_nop 2
	global_load_dword v5, v179, s[22:23] sc1
	v_readlane_b32 s22, v251, 63
	v_readlane_b32 s23, v252, 0
	s_waitcnt vmcnt(0)
	v_add_u32_e32 v16, v16, v5
	s_nop 2
	global_load_dword v6, v179, s[22:23] sc1
	v_readlane_b32 s22, v252, 1
	v_readlane_b32 s23, v252, 2
	s_waitcnt vmcnt(0)
	v_add_u32_e32 v16, v16, v6
	s_nop 2
	global_load_dword v7, v179, s[22:23] sc1
	v_readlane_b32 s22, v252, 3
	v_readlane_b32 s23, v252, 4
	s_waitcnt vmcnt(0)
	v_add_u32_e32 v16, v16, v7
	s_nop 2
	global_load_dword v8, v179, s[22:23] sc1
	v_readlane_b32 s22, v252, 5
	v_readlane_b32 s23, v252, 6
	s_waitcnt vmcnt(0)
	v_add_u32_e32 v16, v16, v8
	s_nop 2
	global_load_dword v9, v179, s[22:23] sc1
	v_readlane_b32 s22, v252, 7
	v_readlane_b32 s23, v252, 8
	s_waitcnt vmcnt(0)
	v_add_u32_e32 v16, v16, v9
	s_nop 2
	global_load_dword v10, v179, s[22:23] sc1
	v_readlane_b32 s22, v252, 9
	v_readlane_b32 s23, v252, 10
	s_waitcnt vmcnt(0)
	v_add_u32_e32 v16, v16, v10
	s_nop 2
	global_load_dword v11, v179, s[22:23] sc1
	v_readlane_b32 s22, v252, 11
	v_readlane_b32 s23, v252, 12
	s_waitcnt vmcnt(0)
	v_add_u32_e32 v16, v16, v11
	s_nop 2
	global_load_dword v12, v179, s[22:23] sc1
	v_readlane_b32 s22, v252, 13
	v_readlane_b32 s23, v252, 14
	s_waitcnt vmcnt(0)
	v_add_u32_e32 v16, v16, v12
	s_nop 2
	global_load_dword v13, v179, s[22:23] sc1
	v_readlane_b32 s22, v252, 15
	v_readlane_b32 s23, v252, 16
	s_waitcnt vmcnt(0)
	v_add_u32_e32 v16, v16, v13
	s_nop 2
	global_load_dword v14, v179, s[22:23] sc1
	v_readlane_b32 s22, v252, 17
	v_readlane_b32 s23, v252, 18
	s_waitcnt vmcnt(0)
	v_add_u32_e32 v16, v16, v14
	s_nop 2
	global_load_dword v15, v179, s[22:23] sc1
	s_waitcnt vmcnt(0)
	v_add_u32_e32 v16, v16, v15
	v_cmp_eq_u32_e32 vcc, s14, v16
	s_cbranch_vccnz .LBB0_3657
	s_and_b32 s14, s7, 0xff
	s_cmp_eq_u32 s14, 0
	s_mov_b64 s[42:43], -1
	s_cbranch_scc1 .LBB0_3662
	s_and_b64 vcc, exec, s[42:43]
	s_cbranch_vccz .LBB0_3657

; __device__ __forceinline__ unsigned xb_ld(unsigned* p)              { return __hip_atomic_load(p, __ATOMIC_RELAXED, __HIP_MEMORY_SCOPE_AGENT); }
; __device__ __forceinline__ unsigned xb_add(unsigned* p, unsigned v) { return __hip_atomic_fetch_add(p, v, __ATOMIC_RELAXED, __HIP_MEMORY_SCOPE_AGENT); }
; #define XB_SPIN(cond, bar) do { unsigned _sp = 0; while (cond) { __builtin_amdgcn_s_sleep(1); \
;     if ((++_sp & 255u) == 0u) { if (xb_ld(&(bar)[XB_TMO])) break; if (_sp > XB_SPIN_CAP) { atomicAdd(&(bar)[XB_TMO], 1u); break; } } } } while (0)
; __device__ __forceinline__ void xcd_barrier(const XcdBarrier& b) {
;     ...
;             else XB_SPIN(xb_ld(&bar[XB_TOPGEN]) == tg, bar);
;             __builtin_amdgcn_fence(__ATOMIC_ACQUIRE, "agent");
;             xb_add(&bar[XB_XGEN(b.x)], 1u);
;             asm volatile("s_waitcnt vmcnt(0)" ::: "memory");
;         } else {
;             XB_SPIN(xb_ld(&bar[XB_XGEN(b.x)]) == gen, bar);
.LBB0_3676:
	s_and_b32 s14, s7, 0xff
	s_mov_b64 s[46:47], -1
	s_cmp_lg_u32 s14, 0
	s_mov_b64 s[50:51], -1
	s_cbranch_scc0 .LBB0_3679
	s_and_b64 vcc, exec, s[50:51]
	s_cbranch_vccz .LBB0_3675

; __device__ __forceinline__ unsigned xb_ld(unsigned* p)              { return __hip_atomic_load(p, __ATOMIC_RELAXED, __HIP_MEMORY_SCOPE_AGENT); }
; __device__ __forceinline__ void xcd_barrier_complete(unsigned* bar, unsigned x, unsigned& nloc, unsigned& nx) {
;     const unsigned G = gridDim.x * gridDim.y * gridDim.z;
;     unsigned sum, cnt, mine, sp = 0u;
;     for (;;) {
;         sum = 0u; cnt = 0u; mine = 0u;
; #pragma unroll
;         for (unsigned j = 0; j < 16; ++j) { const unsigned c = xb_ld(&bar[XB_XCNT(j)]); sum += c; cnt += (c > 0u) ? 1u : 0u; mine = (j == x) ? c : mine; }
;         if (sum == G) break;
;         __builtin_amdgcn_s_sleep(1);
;         if ((++sp & 255u) == 0u) { if (xb_ld(&bar[XB_TMO])) break; if (sp > XB_SPIN_CAP) { atomicAdd(&bar[XB_TMO], 1u); break; } }
;     }
;     nloc = mine > 0u ? mine : 1u; nx = cnt > 0u ? cnt : 1u;
; }
.LBB0_3948:
	v_readlane_b32 s2, v251, 51
	v_readlane_b32 s3, v251, 52
	v_readlane_b32 s6, v255, 18
	s_mov_b64 s[38:39], -1
	s_waitcnt lgkmcnt(0)
	s_nop 1
	global_load_dword v0, v179, s[2:3] sc1
	v_readlane_b32 s2, v251, 53
	v_readlane_b32 s3, v251, 54
	s_nop 4
	global_load_dword v1, v179, s[2:3] sc1
	v_readlane_b32 s2, v251, 55
	v_readlane_b32 s3, v251, 56
	s_waitcnt vmcnt(0)
	v_add_u32_e32 v16, v1, v0
	s_nop 2
	global_load_dword v2, v179, s[2:3] sc1
	v_readlane_b32 s2, v251, 57
	v_readlane_b32 s3, v251, 58
	s_waitcnt vmcnt(0)
	v_add_u32_e32 v16, v16, v2
	s_nop 2
	global_load_dword v3, v179, s[2:3] sc1
	v_readlane_b32 s2, v251, 59
	v_readlane_b32 s3, v251, 60
	s_waitcnt vmcnt(0)
	v_add_u32_e32 v16, v16, v3
	s_nop 2
	global_load_dword v4, v179, s[2:3] sc1
	v_readlane_b32 s2, v251, 61
	v_readlane_b32 s3, v251, 62
	s_waitcnt vmcnt(0)
	v_add_u32_e32 v16, v16, v4
	s_nop 2
	global_load_dword v5, v179, s[2:3] sc1
	v_readlane_b32 s2, v251, 63
	v_readlane_b32 s3, v252, 0
	s_waitcnt vmcnt(0)
	v_add_u32_e32 v16, v16, v5
	s_nop 2
	global_load_dword v6, v179, s[2:3] sc1
	v_readlane_b32 s2, v252, 1
	v_readlane_b32 s3, v252, 2
	s_waitcnt vmcnt(0)
	v_add_u32_e32 v16, v16, v6
	s_nop 2
	global_load_dword v7, v179, s[2:3] sc1
	v_readlane_b32 s2, v252, 3
	v_readlane_b32 s3, v252, 4
	s_waitcnt vmcnt(0)
	v_add_u32_e32 v16, v16, v7
	s_nop 2
	global_load_dword v8, v179, s[2:3] sc1
	v_readlane_b32 s2, v252, 5
	v_readlane_b32 s3, v252, 6
	s_waitcnt vmcnt(0)
	v_add_u32_e32 v16, v16, v8
	s_nop 2
	global_load_dword v9, v179, s[2:3] sc1
	v_readlane_b32 s2, v252, 7
	v_readlane_b32 s3, v252, 8
	s_waitcnt vmcnt(0)
	v_add_u32_e32 v16, v16, v9
	s_nop 2
	global_load_dword v10, v179, s[2:3] sc1
	v_readlane_b32 s2, v252, 9
	v_readlane_b32 s3, v252, 10
	s_waitcnt vmcnt(0)
	v_add_u32_e32 v16, v16, v10
	s_nop 2
	global_load_dword v11, v179, s[2:3] sc1
	v_readlane_b32 s2, v252, 11
	v_readlane_b32 s3, v252, 12
	s_waitcnt vmcnt(0)
	v_add_u32_e32 v16, v16, v11
	s_nop 2
	global_load_dword v12, v179, s[2:3] sc1
	v_readlane_b32 s2, v252, 13
	v_readlane_b32 s3, v252, 14
	s_waitcnt vmcnt(0)
	v_add_u32_e32 v16, v16, v12
	s_nop 2
	global_load_dword v13, v179, s[2:3] sc1
	v_readlane_b32 s2, v252, 15
	v_readlane_b32 s3, v252, 16
	s_waitcnt vmcnt(0)
	v_add_u32_e32 v16, v16, v13
	s_nop 2
	global_load_dword v14, v179, s[2:3] sc1
	v_readlane_b32 s2, v252, 17
	v_readlane_b32 s3, v252, 18
	s_waitcnt vmcnt(0)
	v_add_u32_e32 v16, v16, v14
	s_nop 2
	global_load_dword v15, v179, s[2:3] sc1
	s_mov_b64 s[2:3], -1
	s_waitcnt vmcnt(0)
	v_add_u32_e32 v16, v16, v15
	v_cmp_eq_u32_e32 vcc, s6, v16
	s_cbranch_vccnz .LBB0_3947
	s_and_b32 s2, s4, 0xff
	s_cmp_eq_u32 s2, 0
	s_mov_b64 s[2:3], -1
	s_mov_b64 s[40:41], -1
	s_cbranch_scc1 .LBB0_3952
	s_and_b64 vcc, exec, s[40:41]
	s_cbranch_vccz .LBB0_3947

; __device__ __forceinline__ unsigned xb_ld(unsigned* p)              { return __hip_atomic_load(p, __ATOMIC_RELAXED, __HIP_MEMORY_SCOPE_AGENT); }
; __device__ __forceinline__ unsigned xb_add(unsigned* p, unsigned v) { return __hip_atomic_fetch_add(p, v, __ATOMIC_RELAXED, __HIP_MEMORY_SCOPE_AGENT); }
; #define XB_SPIN(cond, bar) do { unsigned _sp = 0; while (cond) { __builtin_amdgcn_s_sleep(1); \
;     if ((++_sp & 255u) == 0u) { if (xb_ld(&(bar)[XB_TMO])) break; if (_sp > XB_SPIN_CAP) { atomicAdd(&(bar)[XB_TMO], 1u); break; } } } } while (0)
; __device__ __forceinline__ void xcd_barrier(const XcdBarrier& b) {
;     ...
;             else XB_SPIN(xb_ld(&bar[XB_TOPGEN]) == tg, bar);
;             __builtin_amdgcn_fence(__ATOMIC_ACQUIRE, "agent");
;             xb_add(&bar[XB_XGEN(b.x)], 1u);
;             asm volatile("s_waitcnt vmcnt(0)" ::: "memory");
;         } else {
;             XB_SPIN(xb_ld(&bar[XB_XGEN(b.x)]) == gen, bar);
.LBB0_3966:
	s_and_b32 s6, s4, 0xff
	s_mov_b64 s[44:45], -1
	s_cmp_lg_u32 s6, 0
	s_mov_b64 s[48:49], -1
	s_cbranch_scc0 .LBB0_3969
	s_and_b64 vcc, exec, s[48:49]
	s_cbranch_vccz .LBB0_3965
